# grid barrier: L1 invalidate issued right after local arrival; XCD leader releases local workgroups before its own invalidate
# baseline (speedup 1.0000x reference)
.LBB0_6:
	s_or_b64 exec, exec, s[34:35]
	buffer_inv sc1
	s_waitcnt vmcnt(0)

.LBB0_423:
	s_or_b64 exec, exec, s[28:29]
	buffer_inv sc1
	v_cvt_f32_u32_e32 v5, v3
	s_waitcnt vmcnt(1)
	v_readfirstlane_b32 s0, v4
	v_sub_u32_e32 v4, 0, v3
	v_rcp_iflag_f32_e32 v5, v5
	v_add_u32_e32 v6, s0, v1
	v_mul_f32_e32 v5, 0x4f7ffffe, v5
	v_cvt_u32_f32_e32 v5, v5
	v_mul_lo_u32 v1, v4, v5
	v_mul_hi_u32 v1, v5, v1
	v_add_u32_e32 v1, v5, v1
	v_mul_hi_u32 v1, v6, v1
	v_mul_lo_u32 v4, v1, v3
	v_sub_u32_e32 v4, v6, v4
	v_add_u32_e32 v5, 1, v1
	v_cmp_ge_u32_e32 vcc, v4, v3
	s_nop 1
	v_cndmask_b32_e32 v1, v1, v5, vcc
	v_sub_u32_e32 v5, v4, v3
	v_cndmask_b32_e32 v4, v4, v5, vcc
	v_add_u32_e32 v5, 1, v1
	v_cmp_ge_u32_e32 vcc, v4, v3
	v_add_u32_e32 v4, 1, v6
	s_nop 0
	v_cndmask_b32_e32 v1, v1, v5, vcc
	v_mul_lo_u32 v5, v3, v1
	v_add_u32_e32 v3, v5, v3
	v_cmp_ne_u32_e32 vcc, v4, v3
	s_and_saveexec_b64 s[0:1], vcc
	s_xor_b64 s[28:29], exec, s[0:1]
	s_cbranch_execz .LBB0_437
	v_readlane_b32 s0, v248, 36
	v_readlane_b32 s1, v248, 37
	s_waitcnt lgkmcnt(0)
	s_nop 3
	global_load_dword v2, v0, s[0:1] sc1
	s_waitcnt vmcnt(0)
	v_cmp_eq_u32_e32 vcc, v2, v1
	s_and_saveexec_b64 s[34:35], vcc
	s_cbranch_execz .LBB0_436
	s_mov_b32 s0, 1
	s_mov_b64 s[38:39], 0
	s_branch .LBB0_427

.LBB0_436:
	s_or_b64 exec, exec, s[34:35]
	s_waitcnt vmcnt(0)
	s_waitcnt vmcnt(0)

.LBB0_454:
	s_or_b64 exec, exec, s[28:29]
	s_mov_b64 s[28:29], exec
	v_mbcnt_lo_u32_b32 v1, s28, 0
	v_mbcnt_hi_u32_b32 v1, s29, v1
	v_cmp_eq_u32_e32 vcc, 0, v1
	s_waitcnt vmcnt(0)
	s_and_saveexec_b64 s[34:35], vcc
	s_cbranch_execz .LBB0_6
	s_bcnt1_i32_b64 s0, s[28:29]
	v_mov_b32_e32 v1, s0
	v_readlane_b32 s0, v248, 36
	v_readlane_b32 s1, v248, 37
	s_nop 4
	global_atomic_add v0, v1, s[0:1]
	s_branch .LBB0_6
